# P1 tile order rebalanced across workgroups; gla_wave_b fragment loads issued one step ahead; gla_wave_a LDS-staged loads; sample attention spread
# speedup vs baseline: 1.0104x; 1.0060x over previous
.LBB0_143:
	s_add_i32 s71, s71, 1
	s_lshl_b32 s98, s71, 1
	s_lshr_b32 s98, 0xf80, s98
	s_and_b32 s98, s98, 3
	s_lshl_b32 s98, s98, 6
	s_add_i32 s98, s98, s2
	s_and_b32 s98, s98, 0xff
	s_mul_i32 s10, s71, s97
	s_mul_hi_u32 s11, s71, s96
	s_add_i32 s11, s11, s10
	s_mul_i32 s10, s71, s96
	s_add_u32 s10, s10, s98
	s_addc_u32 s11, s11, s3
	v_cmp_gt_i64_e32 vcc, s[10:11], v[162:163]
	v_cmp_lt_i64_e64 s[38:39], s[10:11], v[160:161]
	s_cbranch_vccnz .LBB0_149
	s_ashr_i32 s11, s10, 31
	s_lshr_b32 s11, s11, 29
	s_add_i32 s20, s10, s11
	s_and_b32 s11, s20, -8
	s_sub_i32 s21, s10, s11
	s_cmp_gt_i32 s21, 1
	s_mov_b64 s[10:11], -1
	s_cbranch_scc0 .LBB0_146
	s_mul_i32 s10, s21, 0xd3
	s_add_i32 s22, s10, 2
	s_mov_b64 s[10:11], 0

.LBB0_845:
	s_ashr_i32 s8, s33, 10
	s_lshl_b32 s0, s73, 1
	s_ashr_i32 s9, s8, 31
	s_lshl_b32 s1, s33, 6
	s_and_b32 s23, s0, 0x7f80
	s_ashr_i32 s0, s33, 8
	s_lshl_b64 s[10:11], s[8:9], 14
	s_and_b32 s1, s1, 0x3fc0
	s_and_b32 s22, s0, 3
	s_or_b32 s1, s10, s1
	s_lshl_b32 s76, s22, 8
	v_mov_b32_e32 v1, s11
	v_or_b32_e32 v0, s1, v98
	v_lshl_add_u64 v[24:25], v[104:105], 0, s[76:77]
	v_lshlrev_b64 v[0:1], 10, v[0:1]
	v_mov_b32_e32 v3, s11
	v_or_b32_e32 v2, s1, v110
	v_lshl_add_u64 v[0:1], v[24:25], 0, v[0:1]
	v_lshlrev_b64 v[2:3], 10, v[2:3]
	v_lshl_add_u64 v[2:3], v[24:25], 0, v[2:3]
	global_load_dwordx4 v[32:35], v[0:1], off
	global_load_dwordx4 v[48:51], v[2:3], off
	v_mov_b32_e32 v1, s11
	v_or_b32_e32 v0, s1, v112
	v_lshlrev_b64 v[0:1], 10, v[0:1]
	v_mov_b32_e32 v3, s11
	v_or_b32_e32 v2, s1, v114
	v_lshl_add_u64 v[0:1], v[24:25], 0, v[0:1]
	v_lshlrev_b64 v[2:3], 10, v[2:3]
	v_lshl_add_u64 v[2:3], v[24:25], 0, v[2:3]
	global_load_dwordx4 v[52:55], v[0:1], off
	global_load_dwordx4 v[56:59], v[2:3], off
	v_mov_b32_e32 v1, s11
	v_or_b32_e32 v0, s1, v116
	v_lshlrev_b64 v[0:1], 10, v[0:1]
	v_mov_b32_e32 v3, s11
	v_or_b32_e32 v2, s1, v118
	v_lshl_add_u64 v[0:1], v[24:25], 0, v[0:1]
	v_lshlrev_b64 v[2:3], 10, v[2:3]
	v_lshl_add_u64 v[2:3], v[24:25], 0, v[2:3]
	global_load_dwordx4 v[60:63], v[0:1], off
	global_load_dwordx4 v[76:79], v[2:3], off
	v_mov_b32_e32 v1, s11
	v_or_b32_e32 v0, s1, v120
	v_lshlrev_b64 v[0:1], 10, v[0:1]
	v_mov_b32_e32 v3, s11
	v_or_b32_e32 v2, s1, v122
	v_lshl_add_u64 v[0:1], v[24:25], 0, v[0:1]
	v_lshlrev_b64 v[2:3], 10, v[2:3]
	s_lshl_b32 s76, s22, 7
	v_lshl_add_u64 v[2:3], v[24:25], 0, v[2:3]
	global_load_dwordx4 v[80:83], v[0:1], off
	global_load_dwordx4 v[84:87], v[2:3], off
	v_mov_b32_e32 v1, s11
	v_or_b32_e32 v0, s1, v100
	v_lshl_add_u64 v[192:193], v[106:107], 0, s[76:77]
	v_lshl_add_u64 v[194:195], v[108:109], 0, s[76:77]
	v_lshlrev_b64 v[0:1], 9, v[0:1]
	v_lshl_add_u64 v[2:3], v[192:193], 0, v[0:1]
	v_lshl_add_u64 v[0:1], v[194:195], 0, v[0:1]
	global_load_dwordx4 v[88:91], v[2:3], off
	global_load_dwordx4 v[92:95], v[0:1], off
	v_mov_b32_e32 v1, s11
	v_or_b32_e32 v0, s1, v124
	v_lshlrev_b64 v[0:1], 9, v[0:1]
	v_lshl_add_u64 v[2:3], v[192:193], 0, v[0:1]
	v_lshl_add_u64 v[0:1], v[194:195], 0, v[0:1]
	global_load_dwordx4 v[168:171], v[2:3], off
	global_load_dwordx4 v[172:175], v[0:1], off
	v_mov_b32_e32 v1, s11
	v_or_b32_e32 v0, s1, v126
	v_lshlrev_b64 v[0:1], 9, v[0:1]
	v_lshl_add_u64 v[2:3], v[192:193], 0, v[0:1]
	v_lshl_add_u64 v[0:1], v[194:195], 0, v[0:1]
	global_load_dwordx4 v[176:179], v[2:3], off
	global_load_dwordx4 v[180:183], v[0:1], off
	v_mov_b32_e32 v1, s11
	v_or_b32_e32 v0, s1, v128
	v_lshlrev_b64 v[0:1], 9, v[0:1]
	v_lshl_add_u64 v[2:3], v[192:193], 0, v[0:1]
	v_lshl_add_u64 v[0:1], v[194:195], 0, v[0:1]
	global_load_dwordx4 v[184:187], v[2:3], off
	global_load_dwordx4 v[188:191], v[0:1], off
	v_mov_b32_e32 v1, s11
	v_or_b32_e32 v0, s1, v130
	v_mov_b32_e32 v3, s11
	v_or_b32_e32 v2, s1, v132
	v_mov_b32_e32 v9, s11
	v_or_b32_e32 v8, s1, v134
	v_mov_b32_e32 v11, s11
	v_or_b32_e32 v10, s1, v136
	v_mov_b32_e32 v17, s11
	v_or_b32_e32 v16, s1, v138
	v_mov_b32_e32 v19, s11
	v_or_b32_e32 v18, s1, v140
	v_mov_b32_e32 v27, s11
	v_or_b32_e32 v26, s1, v142
	v_mov_b32_e32 v29, s11
	v_or_b32_e32 v28, s1, v144
	v_mov_b32_e32 v37, s11
	v_or_b32_e32 v36, s1, v146
	v_mov_b32_e32 v45, s11
	v_or_b32_e32 v44, s1, v148
	v_mov_b32_e32 v69, s11
	v_or_b32_e32 v68, s1, v150
	v_lshlrev_b64 v[0:1], 10, v[0:1]
	v_lshlrev_b64 v[2:3], 10, v[2:3]
	v_lshlrev_b64 v[8:9], 10, v[8:9]
	v_lshlrev_b64 v[10:11], 10, v[10:11]
	v_lshlrev_b64 v[16:17], 10, v[16:17]
	v_lshlrev_b64 v[18:19], 10, v[18:19]
	v_lshlrev_b64 v[26:27], 10, v[26:27]
	v_lshlrev_b64 v[28:29], 10, v[28:29]
	v_lshlrev_b64 v[36:37], 9, v[36:37]
	v_lshlrev_b64 v[44:45], 9, v[44:45]
	v_lshlrev_b64 v[68:69], 9, v[68:69]
	v_mov_b32_e32 v197, s11
	v_or_b32_e32 v196, s1, v152
	v_lshl_add_u64 v[0:1], v[24:25], 0, v[0:1]
	v_lshl_add_u64 v[4:5], v[24:25], 0, v[2:3]
	v_lshl_add_u64 v[8:9], v[24:25], 0, v[8:9]
	v_lshl_add_u64 v[12:13], v[24:25], 0, v[10:11]
	v_lshl_add_u64 v[16:17], v[24:25], 0, v[16:17]
	v_lshl_add_u64 v[20:21], v[24:25], 0, v[18:19]
	v_lshl_add_u64 v[26:27], v[24:25], 0, v[26:27]
	v_lshl_add_u64 v[28:29], v[24:25], 0, v[28:29]
	v_lshl_add_u64 v[38:39], v[192:193], 0, v[36:37]
	v_lshl_add_u64 v[40:41], v[194:195], 0, v[36:37]
	v_lshl_add_u64 v[46:47], v[192:193], 0, v[44:45]
	v_lshl_add_u64 v[64:65], v[194:195], 0, v[44:45]
	v_lshl_add_u64 v[70:71], v[192:193], 0, v[68:69]
	v_lshl_add_u64 v[72:73], v[194:195], 0, v[68:69]
	v_lshlrev_b64 v[196:197], 9, v[196:197]
	global_load_dwordx4 v[0:3], v[0:1], off
	s_nop 0
	global_load_dwordx4 v[4:7], v[4:5], off
	s_nop 0
	global_load_dwordx4 v[8:11], v[8:9], off
	s_nop 0
	global_load_dwordx4 v[12:15], v[12:13], off
	s_nop 0
	global_load_dwordx4 v[16:19], v[16:17], off
	s_nop 0
	global_load_dwordx4 v[20:23], v[20:21], off
	s_nop 0
	global_load_dwordx4 v[24:27], v[26:27], off
	s_nop 0
	global_load_dwordx4 v[28:31], v[28:29], off
	s_nop 0
	global_load_dwordx4 v[36:39], v[38:39], off
	s_nop 0
	global_load_dwordx4 v[40:43], v[40:41], off
	s_nop 0
	global_load_dwordx4 v[44:47], v[46:47], off
	s_nop 0
	global_load_dwordx4 v[64:67], v[64:65], off
	s_nop 0
	global_load_dwordx4 v[68:71], v[70:71], off
	s_nop 0
	global_load_dwordx4 v[72:75], v[72:73], off
	v_lshl_add_u64 v[192:193], v[192:193], 0, v[196:197]
	s_waitcnt vmcnt(29)
	ds_write_b128 v125, v[32:35]
	s_waitcnt vmcnt(28)
	ds_write_b128 v125, v[48:51] offset:1088
	s_waitcnt vmcnt(27)
	ds_write_b128 v125, v[52:55] offset:2176
	s_waitcnt vmcnt(26)
	ds_write_b128 v125, v[56:59] offset:3264
	s_waitcnt vmcnt(25)
	ds_write_b128 v125, v[60:63] offset:4352
	s_waitcnt vmcnt(24)
	ds_write_b128 v125, v[76:79] offset:5440
	s_waitcnt vmcnt(23)
	ds_write_b128 v125, v[80:83] offset:6528
	s_waitcnt vmcnt(22)
	ds_write_b128 v125, v[84:87] offset:7616
	s_waitcnt vmcnt(21)
	ds_write_b128 v127, v[88:91] offset:8704
	s_waitcnt vmcnt(20)
	ds_write_b128 v127, v[92:95] offset:13312
	s_waitcnt vmcnt(19)
	ds_write_b128 v127, v[168:171] offset:9856
	s_waitcnt vmcnt(18)
	ds_write_b128 v127, v[172:175] offset:14464
	s_waitcnt vmcnt(17)
	ds_write_b128 v127, v[176:179] offset:11008
	s_waitcnt vmcnt(16)
	ds_write_b128 v127, v[180:183] offset:15616
	s_waitcnt vmcnt(15)
	ds_write_b128 v127, v[184:187] offset:12160
	s_waitcnt vmcnt(14)
	ds_write_b128 v127, v[188:191] offset:16768
	v_add_u32_e32 v143, v99, v101
	v_lshl_add_u64 v[194:195], v[194:195], 0, v[196:197]
	ds_read_b128 v[32:35], v143
	global_load_dwordx4 v[76:79], v[192:193], off
	global_load_dwordx4 v[92:95], v[194:195], off
	ds_read_b128 v[48:51], v143 offset:16
	ds_read_b128 v[52:55], v129 offset:8704
	ds_read_b128 v[56:59], v129 offset:13312
	s_ashr_i32 s1, s0, 31
	s_lshl_b64 s[0:1], s[0:1], 22
	s_waitcnt lgkmcnt(3)
	v_mul_f32_e32 v32, 0x3fb8aa3b, v32
	v_mul_f32_e32 v33, 0x3fb8aa3b, v33
	v_exp_f32_e32 v32, v32
	v_exp_f32_e32 v33, v33
	v_mul_f32_e32 v34, 0x3fb8aa3b, v34
	v_mul_f32_e32 v35, 0x3fb8aa3b, v35
	v_exp_f32_e32 v34, v34
	v_exp_f32_e32 v35, v35
	v_rcp_f32_e32 v62, v32
	v_rcp_f32_e32 v63, v33
	s_waitcnt lgkmcnt(1)
	v_lshlrev_b32_e32 v60, 16, v52
	v_and_b32_e32 v61, 0xffff0000, v52
	v_mul_f32_e32 v48, 0x3fb8aa3b, v48
	v_mul_f32_e32 v49, 0x3fb8aa3b, v49
	v_pk_mul_f32 v[32:33], v[32:33], v[60:61]
	s_waitcnt lgkmcnt(0)
	v_lshlrev_b32_e32 v60, 16, v56
	v_and_b32_e32 v61, 0xffff0000, v56
	v_exp_f32_e32 v48, v48
	v_exp_f32_e32 v49, v49
	v_pk_mul_f32 v[60:61], v[62:63], v[60:61]
	v_rcp_f32_e32 v62, v34
	v_rcp_f32_e32 v63, v35
	v_lshlrev_b32_e32 v52, 16, v53
	v_and_b32_e32 v53, 0xffff0000, v53
	v_mul_f32_e32 v50, 0x3fb8aa3b, v50
	v_mul_f32_e32 v51, 0x3fb8aa3b, v51
	v_pk_mul_f32 v[34:35], v[34:35], v[52:53]
	v_lshlrev_b32_e32 v52, 16, v57
	v_and_b32_e32 v53, 0xffff0000, v57
	v_exp_f32_e32 v50, v50
	v_exp_f32_e32 v51, v51
	v_pk_mul_f32 v[52:53], v[62:63], v[52:53]
	v_rcp_f32_e32 v62, v48
	v_rcp_f32_e32 v63, v49
	v_lshlrev_b32_e32 v56, 16, v54
	v_and_b32_e32 v57, 0xffff0000, v54
	v_pk_mul_f32 v[56:57], v[48:49], v[56:57]
	v_lshlrev_b32_e32 v48, 16, v58
	v_and_b32_e32 v49, 0xffff0000, v58
	v_pk_mul_f32 v[62:63], v[62:63], v[48:49]
	v_lshlrev_b32_e32 v48, 16, v55
	v_and_b32_e32 v49, 0xffff0000, v55
	v_rcp_f32_e32 v54, v50
	v_rcp_f32_e32 v55, v51
	v_pk_mul_f32 v[80:81], v[50:51], v[48:49]
	v_lshlrev_b32_e32 v48, 16, v59
	v_and_b32_e32 v49, 0xffff0000, v59
	v_pk_mul_f32 v[58:59], v[54:55], v[48:49]
	v_cvt_pk_bf16_f32 v48, v32, v33
	v_cvt_pk_bf16_f32 v33, v52, v53
	ds_read_b128 v[52:55], v131
	v_cvt_pk_bf16_f32 v49, v34, v35
	v_cvt_pk_bf16_f32 v50, v56, v57
	v_cvt_pk_bf16_f32 v51, v80, v81
	v_cvt_pk_bf16_f32 v32, v60, v61
	s_waitcnt lgkmcnt(0)
	v_mul_f32_e32 v52, 0x3fb8aa3b, v52
	v_mul_f32_e32 v53, 0x3fb8aa3b, v53
	v_exp_f32_e32 v52, v52
	v_exp_f32_e32 v53, v53
	v_cvt_pk_bf16_f32 v34, v62, v63
	v_cvt_pk_bf16_f32 v35, v58, v59
	ds_read_b128 v[56:59], v131 offset:16
	ds_read_b128 v[60:63], v133 offset:8704
	ds_read_b128 v[80:83], v133 offset:13312
	v_mul_f32_e32 v54, 0x3fb8aa3b, v54
	v_mul_f32_e32 v55, 0x3fb8aa3b, v55
	v_exp_f32_e32 v54, v54
	v_exp_f32_e32 v55, v55
	v_rcp_f32_e32 v86, v52
	v_rcp_f32_e32 v87, v53
	s_waitcnt lgkmcnt(1)
	v_lshlrev_b32_e32 v84, 16, v60
	v_and_b32_e32 v85, 0xffff0000, v60
	v_mul_f32_e32 v56, 0x3fb8aa3b, v56
	v_mul_f32_e32 v57, 0x3fb8aa3b, v57
	v_pk_mul_f32 v[52:53], v[52:53], v[84:85]
	s_waitcnt lgkmcnt(0)
	v_lshlrev_b32_e32 v84, 16, v80
	v_and_b32_e32 v85, 0xffff0000, v80
	v_exp_f32_e32 v56, v56
	v_exp_f32_e32 v57, v57
	v_pk_mul_f32 v[84:85], v[86:87], v[84:85]
	v_rcp_f32_e32 v86, v54
	v_rcp_f32_e32 v87, v55
	v_lshlrev_b32_e32 v60, 16, v61
	v_and_b32_e32 v61, 0xffff0000, v61
	v_mul_f32_e32 v58, 0x3fb8aa3b, v58
	v_mul_f32_e32 v59, 0x3fb8aa3b, v59
	v_pk_mul_f32 v[54:55], v[54:55], v[60:61]
	v_lshlrev_b32_e32 v60, 16, v81
	v_and_b32_e32 v61, 0xffff0000, v81
	v_exp_f32_e32 v58, v58
	v_exp_f32_e32 v59, v59
	v_pk_mul_f32 v[60:61], v[86:87], v[60:61]
	v_rcp_f32_e32 v86, v56
	v_rcp_f32_e32 v87, v57
	v_lshlrev_b32_e32 v80, 16, v62
	v_and_b32_e32 v81, 0xffff0000, v62
	v_pk_mul_f32 v[56:57], v[56:57], v[80:81]
	v_lshlrev_b32_e32 v80, 16, v82
	v_and_b32_e32 v81, 0xffff0000, v82
	v_lshlrev_b32_e32 v62, 16, v63
	v_and_b32_e32 v63, 0xffff0000, v63
	v_pk_mul_f32 v[86:87], v[86:87], v[80:81]
	v_rcp_f32_e32 v80, v58
	v_rcp_f32_e32 v81, v59
	v_pk_mul_f32 v[58:59], v[58:59], v[62:63]
	v_cvt_pk_bf16_f32 v52, v52, v53
	v_cvt_pk_bf16_f32 v53, v54, v55
	v_cvt_pk_bf16_f32 v54, v56, v57
	v_cvt_pk_bf16_f32 v55, v58, v59
	ds_read_b128 v[56:59], v135
	v_lshlrev_b32_e32 v62, 16, v83
	v_and_b32_e32 v63, 0xffff0000, v83
	v_pk_mul_f32 v[62:63], v[80:81], v[62:63]
	v_cvt_pk_bf16_f32 v80, v84, v85
	s_waitcnt lgkmcnt(0)
	v_mul_f32_e32 v56, 0x3fb8aa3b, v56
	v_mul_f32_e32 v57, 0x3fb8aa3b, v57
	v_exp_f32_e32 v56, v56
	v_exp_f32_e32 v57, v57
	v_cvt_pk_bf16_f32 v81, v60, v61
	v_cvt_pk_bf16_f32 v82, v86, v87
	v_cvt_pk_bf16_f32 v83, v62, v63
	ds_read_b128 v[60:63], v135 offset:16
	ds_read_b128 v[84:87], v137 offset:8704
	ds_read_b128 v[88:91], v137 offset:13312
	v_mul_f32_e32 v58, 0x3fb8aa3b, v58
	v_mul_f32_e32 v59, 0x3fb8aa3b, v59
	v_exp_f32_e32 v58, v58
	v_exp_f32_e32 v59, v59
	v_rcp_f32_e32 v170, v56
	v_rcp_f32_e32 v171, v57
	s_waitcnt lgkmcnt(1)
	v_lshlrev_b32_e32 v168, 16, v84
	v_and_b32_e32 v169, 0xffff0000, v84
	v_mul_f32_e32 v60, 0x3fb8aa3b, v60
	v_mul_f32_e32 v61, 0x3fb8aa3b, v61
	v_pk_mul_f32 v[56:57], v[56:57], v[168:169]
	s_waitcnt lgkmcnt(0)
	v_lshlrev_b32_e32 v168, 16, v88
	v_and_b32_e32 v169, 0xffff0000, v88
	v_exp_f32_e32 v60, v60
	v_exp_f32_e32 v61, v61
	v_pk_mul_f32 v[168:169], v[170:171], v[168:169]
	v_rcp_f32_e32 v170, v58
	v_rcp_f32_e32 v171, v59
	v_lshlrev_b32_e32 v84, 16, v85
	v_and_b32_e32 v85, 0xffff0000, v85
	v_mul_f32_e32 v62, 0x3fb8aa3b, v62
	v_mul_f32_e32 v63, 0x3fb8aa3b, v63
	v_pk_mul_f32 v[58:59], v[58:59], v[84:85]
	v_lshlrev_b32_e32 v84, 16, v89
	v_and_b32_e32 v85, 0xffff0000, v89
	v_exp_f32_e32 v62, v62
	v_exp_f32_e32 v63, v63
	v_pk_mul_f32 v[88:89], v[170:171], v[84:85]
	v_rcp_f32_e32 v170, v60
	v_rcp_f32_e32 v171, v61
	v_lshlrev_b32_e32 v84, 16, v86
	v_and_b32_e32 v85, 0xffff0000, v86
	v_pk_mul_f32 v[60:61], v[60:61], v[84:85]
	v_lshlrev_b32_e32 v84, 16, v90
	v_and_b32_e32 v85, 0xffff0000, v90
	v_pk_mul_f32 v[170:171], v[170:171], v[84:85]
	v_lshlrev_b32_e32 v84, 16, v87
	v_and_b32_e32 v85, 0xffff0000, v87
	v_rcp_f32_e32 v86, v62
	v_rcp_f32_e32 v87, v63
	v_pk_mul_f32 v[62:63], v[62:63], v[84:85]
	v_lshlrev_b32_e32 v84, 16, v91
	v_and_b32_e32 v85, 0xffff0000, v91
	v_pk_mul_f32 v[90:91], v[86:87], v[84:85]
	v_cvt_pk_bf16_f32 v56, v56, v57
	v_cvt_pk_bf16_f32 v57, v58, v59
	v_cvt_pk_bf16_f32 v58, v60, v61
	v_cvt_pk_bf16_f32 v59, v62, v63
	v_cvt_pk_bf16_f32 v84, v168, v169
	v_cvt_pk_bf16_f32 v85, v88, v89
	v_cvt_pk_bf16_f32 v86, v170, v171
	ds_read_b128 v[60:63], v139
	v_cvt_pk_bf16_f32 v87, v90, v91
	ds_read_b128 v[88:91], v139 offset:16
	ds_read_b128 v[168:171], v141 offset:8704
	ds_read_b128 v[172:175], v141 offset:13312
	s_waitcnt vmcnt(15)
	ds_write_b128 v125, v[0:3]
	s_waitcnt vmcnt(14)
	ds_write_b128 v125, v[4:7] offset:1088
	s_waitcnt vmcnt(13)
	ds_write_b128 v125, v[8:11] offset:2176
	s_waitcnt vmcnt(12)
	ds_write_b128 v125, v[12:15] offset:3264
	s_waitcnt vmcnt(11)
	ds_write_b128 v125, v[16:19] offset:4352
	s_waitcnt vmcnt(10)
	ds_write_b128 v125, v[20:23] offset:5440
	s_waitcnt vmcnt(9)
	ds_write_b128 v125, v[24:27] offset:6528
	s_waitcnt vmcnt(8)
	ds_write_b128 v125, v[28:31] offset:7616
	s_waitcnt vmcnt(7)
	ds_write_b128 v127, v[36:39] offset:8704
	s_waitcnt vmcnt(6)
	ds_write_b128 v127, v[40:43] offset:13312
	s_waitcnt vmcnt(5)
	ds_write_b128 v127, v[44:47] offset:9856
	s_waitcnt vmcnt(4)
	ds_write_b128 v127, v[64:67] offset:14464
	s_waitcnt vmcnt(3)
	ds_write_b128 v127, v[68:71] offset:11008
	s_waitcnt vmcnt(2)
	ds_write_b128 v127, v[72:75] offset:15616
	s_waitcnt vmcnt(1)
	ds_write_b128 v127, v[76:79] offset:12160
	s_waitcnt vmcnt(0)
	ds_write_b128 v127, v[92:95] offset:16768
	ds_read_b128 v[0:3], v143
	ds_read_b128 v[4:7], v143 offset:16
	ds_read_b128 v[8:11], v129 offset:8704
	ds_read_b128 v[12:15], v129 offset:13312
	s_waitcnt lgkmcnt(14)
	v_mul_f32_e32 v60, 0x3fb8aa3b, v60
	v_mul_f32_e32 v61, 0x3fb8aa3b, v61
	s_waitcnt lgkmcnt(2)
	v_mul_f32_e32 v4, 0x3fb8aa3b, v4
	v_mul_f32_e32 v0, 0x3fb8aa3b, v0
	v_mul_f32_e32 v1, 0x3fb8aa3b, v1
	v_exp_f32_e32 v0, v0
	v_exp_f32_e32 v1, v1
	v_mul_f32_e32 v2, 0x3fb8aa3b, v2
	v_mul_f32_e32 v3, 0x3fb8aa3b, v3
	v_exp_f32_e32 v2, v2
	v_exp_f32_e32 v3, v3
	v_rcp_f32_e32 v18, v0
	v_rcp_f32_e32 v19, v1
	s_waitcnt lgkmcnt(1)
	v_lshlrev_b32_e32 v16, 16, v8
	v_and_b32_e32 v17, 0xffff0000, v8
	v_mul_f32_e32 v5, 0x3fb8aa3b, v5
	v_pk_mul_f32 v[0:1], v[0:1], v[16:17]
	s_waitcnt lgkmcnt(0)
	v_lshlrev_b32_e32 v16, 16, v12
	v_and_b32_e32 v17, 0xffff0000, v12
	v_exp_f32_e32 v4, v4
	v_exp_f32_e32 v5, v5
	v_pk_mul_f32 v[16:17], v[18:19], v[16:17]
	v_rcp_f32_e32 v18, v2
	v_rcp_f32_e32 v19, v3
	v_lshlrev_b32_e32 v8, 16, v9
	v_and_b32_e32 v9, 0xffff0000, v9
	v_mul_f32_e32 v6, 0x3fb8aa3b, v6
	v_mul_f32_e32 v7, 0x3fb8aa3b, v7
	v_pk_mul_f32 v[2:3], v[2:3], v[8:9]
	v_lshlrev_b32_e32 v8, 16, v13
	v_and_b32_e32 v9, 0xffff0000, v13
	v_exp_f32_e32 v6, v6
	v_exp_f32_e32 v7, v7
	v_pk_mul_f32 v[8:9], v[18:19], v[8:9]
	v_rcp_f32_e32 v18, v4
	v_rcp_f32_e32 v19, v5
	v_cvt_pk_bf16_f32 v64, v0, v1
	v_cvt_pk_bf16_f32 v65, v2, v3
	ds_read_b128 v[0:3], v131
	v_lshlrev_b32_e32 v12, 16, v10
	v_and_b32_e32 v13, 0xffff0000, v10
	v_pk_mul_f32 v[4:5], v[4:5], v[12:13]
	v_lshlrev_b32_e32 v12, 16, v14
	v_and_b32_e32 v13, 0xffff0000, v14
	v_pk_mul_f32 v[12:13], v[18:19], v[12:13]
	v_rcp_f32_e32 v18, v6
	v_rcp_f32_e32 v19, v7
	v_lshlrev_b32_e32 v10, 16, v11
	v_and_b32_e32 v11, 0xffff0000, v11
	s_waitcnt lgkmcnt(0)
	v_mul_f32_e32 v0, 0x3fb8aa3b, v0
	v_mul_f32_e32 v1, 0x3fb8aa3b, v1
	v_pk_mul_f32 v[6:7], v[6:7], v[10:11]
	v_lshlrev_b32_e32 v10, 16, v15
	v_and_b32_e32 v11, 0xffff0000, v15
	v_exp_f32_e32 v0, v0
	v_exp_f32_e32 v1, v1
	v_pk_mul_f32 v[10:11], v[18:19], v[10:11]
	v_cvt_pk_bf16_f32 v66, v4, v5
	v_cvt_pk_bf16_f32 v67, v6, v7
	v_cvt_pk_bf16_f32 v16, v16, v17
	v_cvt_pk_bf16_f32 v17, v8, v9
	v_cvt_pk_bf16_f32 v18, v12, v13
	v_cvt_pk_bf16_f32 v19, v10, v11
	ds_read_b128 v[4:7], v131 offset:16
	ds_read_b128 v[8:11], v133 offset:8704
	ds_read_b128 v[12:15], v133 offset:13312
	v_mul_f32_e32 v2, 0x3fb8aa3b, v2
	v_mul_f32_e32 v3, 0x3fb8aa3b, v3
	v_exp_f32_e32 v2, v2
	v_exp_f32_e32 v3, v3
	v_rcp_f32_e32 v22, v0
	v_rcp_f32_e32 v23, v1
	s_waitcnt lgkmcnt(1)
	v_lshlrev_b32_e32 v20, 16, v8
	v_and_b32_e32 v21, 0xffff0000, v8
	v_mul_f32_e32 v4, 0x3fb8aa3b, v4
	v_mul_f32_e32 v5, 0x3fb8aa3b, v5
	v_pk_mul_f32 v[0:1], v[0:1], v[20:21]
	s_waitcnt lgkmcnt(0)
	v_lshlrev_b32_e32 v20, 16, v12
	v_and_b32_e32 v21, 0xffff0000, v12
	v_exp_f32_e32 v4, v4
	v_exp_f32_e32 v5, v5
	v_pk_mul_f32 v[20:21], v[22:23], v[20:21]
	v_rcp_f32_e32 v22, v2
	v_rcp_f32_e32 v23, v3
	v_lshlrev_b32_e32 v8, 16, v9
	v_and_b32_e32 v9, 0xffff0000, v9
	v_mul_f32_e32 v6, 0x3fb8aa3b, v6
	v_mul_f32_e32 v7, 0x3fb8aa3b, v7
	v_pk_mul_f32 v[2:3], v[2:3], v[8:9]
	v_lshlrev_b32_e32 v8, 16, v13
	v_and_b32_e32 v9, 0xffff0000, v13
	v_exp_f32_e32 v6, v6
	v_exp_f32_e32 v7, v7
	v_pk_mul_f32 v[8:9], v[22:23], v[8:9]
	v_rcp_f32_e32 v22, v4
	v_rcp_f32_e32 v23, v5
	v_cvt_pk_bf16_f32 v68, v0, v1
	v_cvt_pk_bf16_f32 v69, v2, v3
	ds_read_b128 v[0:3], v135
	v_lshlrev_b32_e32 v12, 16, v10
	v_and_b32_e32 v13, 0xffff0000, v10
	v_pk_mul_f32 v[4:5], v[4:5], v[12:13]
	v_lshlrev_b32_e32 v12, 16, v14
	v_and_b32_e32 v13, 0xffff0000, v14
	v_pk_mul_f32 v[12:13], v[22:23], v[12:13]
	v_rcp_f32_e32 v22, v6
	v_rcp_f32_e32 v23, v7
	v_lshlrev_b32_e32 v10, 16, v11
	v_and_b32_e32 v11, 0xffff0000, v11
	s_waitcnt lgkmcnt(0)
	v_mul_f32_e32 v0, 0x3fb8aa3b, v0
	v_mul_f32_e32 v1, 0x3fb8aa3b, v1
	v_pk_mul_f32 v[6:7], v[6:7], v[10:11]
	v_lshlrev_b32_e32 v10, 16, v15
	v_and_b32_e32 v11, 0xffff0000, v15
	v_exp_f32_e32 v0, v0
	v_exp_f32_e32 v1, v1
	v_pk_mul_f32 v[10:11], v[22:23], v[10:11]
	v_cvt_pk_bf16_f32 v70, v4, v5
	v_cvt_pk_bf16_f32 v71, v6, v7
	v_cvt_pk_bf16_f32 v37, v8, v9
	v_cvt_pk_bf16_f32 v38, v12, v13
	v_cvt_pk_bf16_f32 v39, v10, v11
	ds_read_b128 v[4:7], v135 offset:16
	ds_read_b128 v[8:11], v137 offset:8704
	ds_read_b128 v[12:15], v137 offset:13312
	v_mul_f32_e32 v2, 0x3fb8aa3b, v2
	v_mul_f32_e32 v3, 0x3fb8aa3b, v3
	v_exp_f32_e32 v2, v2
	v_exp_f32_e32 v3, v3
	v_rcp_f32_e32 v22, v0
	v_rcp_f32_e32 v23, v1
	v_exp_f32_e32 v60, v60
	v_exp_f32_e32 v61, v61
	v_cvt_pk_bf16_f32 v36, v20, v21
	s_waitcnt lgkmcnt(1)
	v_lshlrev_b32_e32 v20, 16, v8
	v_and_b32_e32 v21, 0xffff0000, v8
	v_mul_f32_e32 v4, 0x3fb8aa3b, v4
	v_mul_f32_e32 v5, 0x3fb8aa3b, v5
	v_pk_mul_f32 v[0:1], v[0:1], v[20:21]
	s_waitcnt lgkmcnt(0)
	v_lshlrev_b32_e32 v20, 16, v12
	v_and_b32_e32 v21, 0xffff0000, v12
	v_exp_f32_e32 v4, v4
	v_exp_f32_e32 v5, v5
	v_pk_mul_f32 v[20:21], v[22:23], v[20:21]
	v_rcp_f32_e32 v22, v2
	v_rcp_f32_e32 v23, v3
	v_mul_f32_e32 v62, 0x3fb8aa3b, v62
	v_mul_f32_e32 v63, 0x3fb8aa3b, v63
	v_exp_f32_e32 v62, v62
	v_exp_f32_e32 v63, v63
	v_rcp_f32_e32 v178, v60
	v_rcp_f32_e32 v179, v61
	v_lshlrev_b32_e32 v8, 16, v9
	v_and_b32_e32 v9, 0xffff0000, v9
	v_mul_f32_e32 v6, 0x3fb8aa3b, v6
	v_mul_f32_e32 v7, 0x3fb8aa3b, v7
	v_pk_mul_f32 v[2:3], v[2:3], v[8:9]
	v_lshlrev_b32_e32 v8, 16, v13
	v_and_b32_e32 v9, 0xffff0000, v13
	v_lshlrev_b32_e32 v176, 16, v168
	v_and_b32_e32 v177, 0xffff0000, v168
	v_exp_f32_e32 v6, v6
	v_exp_f32_e32 v7, v7
	v_pk_mul_f32 v[8:9], v[22:23], v[8:9]
	v_rcp_f32_e32 v22, v4
	v_rcp_f32_e32 v23, v5
	v_mul_f32_e32 v88, 0x3fb8aa3b, v88
	v_mul_f32_e32 v89, 0x3fb8aa3b, v89
	v_pk_mul_f32 v[60:61], v[60:61], v[176:177]
	v_lshlrev_b32_e32 v176, 16, v172
	v_and_b32_e32 v177, 0xffff0000, v172
	v_exp_f32_e32 v88, v88
	v_exp_f32_e32 v89, v89
	v_pk_mul_f32 v[176:177], v[178:179], v[176:177]
	v_rcp_f32_e32 v178, v62
	v_rcp_f32_e32 v179, v63
	v_lshlrev_b32_e32 v12, 16, v10
	v_and_b32_e32 v13, 0xffff0000, v10
	v_pk_mul_f32 v[4:5], v[4:5], v[12:13]
	v_lshlrev_b32_e32 v12, 16, v14
	v_and_b32_e32 v13, 0xffff0000, v14
	v_lshlrev_b32_e32 v168, 16, v169
	v_and_b32_e32 v169, 0xffff0000, v169
	v_pk_mul_f32 v[12:13], v[22:23], v[12:13]
	v_rcp_f32_e32 v22, v6
	v_rcp_f32_e32 v23, v7
	v_mul_f32_e32 v90, 0x3fb8aa3b, v90
	v_mul_f32_e32 v91, 0x3fb8aa3b, v91
	v_pk_mul_f32 v[62:63], v[62:63], v[168:169]
	v_lshlrev_b32_e32 v168, 16, v173
	v_and_b32_e32 v169, 0xffff0000, v173
	v_exp_f32_e32 v90, v90
	v_exp_f32_e32 v91, v91
	v_pk_mul_f32 v[168:169], v[178:179], v[168:169]
	v_rcp_f32_e32 v178, v88
	v_rcp_f32_e32 v179, v89
	v_lshlrev_b32_e32 v10, 16, v11
	v_and_b32_e32 v11, 0xffff0000, v11
	v_pk_mul_f32 v[6:7], v[6:7], v[10:11]
	v_lshlrev_b32_e32 v10, 16, v15
	v_and_b32_e32 v11, 0xffff0000, v15
	v_lshlrev_b32_e32 v172, 16, v170
	v_and_b32_e32 v173, 0xffff0000, v170
	v_pk_mul_f32 v[10:11], v[22:23], v[10:11]
	v_cvt_pk_bf16_f32 v40, v20, v21
	ds_read_b128 v[20:23], v139
	v_pk_mul_f32 v[88:89], v[88:89], v[172:173]
	v_lshlrev_b32_e32 v172, 16, v174
	v_and_b32_e32 v173, 0xffff0000, v174
	v_pk_mul_f32 v[172:173], v[178:179], v[172:173]
	v_rcp_f32_e32 v178, v90
	v_rcp_f32_e32 v179, v91
	ds_read_b128 v[44:47], v139 offset:16
	ds_read_b128 v[76:79], v141 offset:8704
	ds_read_b128 v[92:95], v141 offset:13312
	v_lshlrev_b32_e32 v170, 16, v171
	v_and_b32_e32 v171, 0xffff0000, v171
	v_pk_mul_f32 v[90:91], v[90:91], v[170:171]
	v_lshlrev_b32_e32 v170, 16, v175
	v_and_b32_e32 v171, 0xffff0000, v175
	v_cvt_pk_bf16_f32 v72, v0, v1
	s_waitcnt lgkmcnt(3)
	v_mul_f32_e32 v0, 0x3fb8aa3b, v20
	s_waitcnt lgkmcnt(2)
	v_mul_f32_e32 v20, 0x3fb8aa3b, v45
	v_pk_mul_f32 v[170:171], v[178:179], v[170:171]
	v_exp_f32_e32 v45, v20
	v_mul_f32_e32 v20, 0x3fb8aa3b, v22
	v_cvt_pk_bf16_f32 v60, v60, v61
	v_cvt_pk_bf16_f32 v61, v62, v63
	v_cvt_pk_bf16_f32 v63, v90, v91
	v_cvt_pk_bf16_f32 v91, v170, v171
	v_exp_f32_e32 v170, v20
	v_mul_f32_e32 v20, 0x3fb8aa3b, v46
	v_cvt_pk_bf16_f32 v62, v88, v89
	v_cvt_pk_bf16_f32 v89, v168, v169
	v_exp_f32_e32 v168, v0
	v_mul_f32_e32 v0, 0x3fb8aa3b, v44
	v_exp_f32_e32 v46, v20
	v_mul_f32_e32 v20, 0x3fb8aa3b, v23
	v_exp_f32_e32 v44, v0
	v_mul_f32_e32 v0, 0x3fb8aa3b, v21
	v_exp_f32_e32 v171, v20
	v_mfma_f32_32x32x16_bf16 v[16:31], v[16:19], v[64:67], 0
	v_exp_f32_e32 v169, v0
	v_cvt_pk_bf16_f32 v90, v172, v173
	s_waitcnt lgkmcnt(1)
	v_lshlrev_b32_e32 v172, 16, v76
	v_and_b32_e32 v173, 0xffff0000, v76
	v_pk_mul_f32 v[172:173], v[168:169], v[172:173]
	v_rcp_f32_e32 v168, v168
	v_rcp_f32_e32 v169, v169
	v_mfma_f32_32x32x16_bf16 v[16:31], v[36:39], v[68:71], v[16:31]
	v_cvt_pk_bf16_f32 v41, v8, v9
	v_cvt_pk_bf16_f32 v42, v12, v13
	v_cvt_pk_bf16_f32 v43, v10, v11
	v_mul_f32_e32 v47, 0x3fb8aa3b, v47
	s_waitcnt lgkmcnt(0)
	v_lshlrev_b32_e32 v174, 16, v92
	v_and_b32_e32 v175, 0xffff0000, v92
	v_exp_f32_e32 v47, v47
	v_pk_mul_f32 v[168:169], v[168:169], v[174:175]
	v_rcp_f32_e32 v174, v170
	v_rcp_f32_e32 v175, v171
	v_lshlrev_b32_e32 v76, 16, v77
	v_and_b32_e32 v77, 0xffff0000, v77
	v_pk_mul_f32 v[170:171], v[170:171], v[76:77]
	v_rcp_f32_e32 v76, v44
	v_rcp_f32_e32 v77, v45
	v_cvt_pk_bf16_f32 v73, v2, v3
	v_cvt_pk_bf16_f32 v74, v4, v5
	v_cvt_pk_bf16_f32 v75, v6, v7
	v_lshlrev_b32_e32 v36, 16, v93
	v_and_b32_e32 v37, 0xffff0000, v93
	v_pk_mul_f32 v[38:39], v[174:175], v[36:37]
	v_lshlrev_b32_e32 v36, 16, v78
	v_and_b32_e32 v37, 0xffff0000, v78
	v_mfma_f32_32x32x16_bf16 v[16:31], v[40:43], v[72:75], v[16:31]
	v_rcp_f32_e32 v40, v46
	v_rcp_f32_e32 v41, v47
	v_pk_mul_f32 v[44:45], v[44:45], v[36:37]
	v_lshlrev_b32_e32 v36, 16, v94
	v_and_b32_e32 v37, 0xffff0000, v94
	v_pk_mul_f32 v[76:77], v[76:77], v[36:37]
	v_lshlrev_b32_e32 v36, 16, v79
	v_and_b32_e32 v37, 0xffff0000, v79
	v_pk_mul_f32 v[42:43], v[46:47], v[36:37]
	v_lshlrev_b32_e32 v36, 16, v95
	v_and_b32_e32 v37, 0xffff0000, v95
	v_pk_mul_f32 v[40:41], v[40:41], v[36:37]
	v_cvt_pk_bf16_f32 v36, v168, v169
	v_cvt_pk_bf16_f32 v37, v38, v39
	v_cvt_pk_bf16_f32 v38, v76, v77
	v_cvt_pk_bf16_f32 v39, v40, v41
	v_mfma_f32_32x32x16_bf16 v[0:15], v[32:35], v[48:51], 0
	v_cvt_pk_bf16_f32 v76, v172, v173
	v_cvt_pk_bf16_f32 v77, v170, v171
	v_cvt_pk_bf16_f32 v78, v44, v45
	v_cvt_pk_bf16_f32 v79, v42, v43
	v_cvt_pk_bf16_f32 v88, v176, v177
	s_or_b32 s0, s0, s23
	s_bfe_u32 s21, s73, 0x80006
	v_mfma_f32_32x32x16_bf16 v[16:31], v[36:39], v[76:79], v[16:31]
	v_mov_b32_e32 v92, 0
	v_mov_b32_e32 v93, v103
	v_mfma_f32_32x32x16_bf16 v[32:47], v[32:35], v[64:67], 0
	s_nop 8
	v_cndmask_b32_e64 v16, v16, 0, s[38:39]
	v_cndmask_b32_e64 v17, 0, v17, s[40:41]
	v_cndmask_b32_e64 v18, v18, 0, s[42:43]
	v_cndmask_b32_e64 v19, v19, 0, s[44:45]
	v_cndmask_b32_e64 v20, v20, 0, s[46:47]
	v_cndmask_b32_e64 v21, v21, 0, s[48:49]
	v_cndmask_b32_e64 v22, v22, 0, s[50:51]
	v_mfma_f32_32x32x16_bf16 v[0:15], v[80:83], v[52:55], v[0:15]
	v_cndmask_b32_e64 v23, v23, 0, s[52:53]
	v_cndmask_b32_e64 v24, v24, 0, s[54:55]
	v_cndmask_b32_e64 v25, v25, 0, s[56:57]
	v_cndmask_b32_e64 v26, v26, 0, s[58:59]
	v_cndmask_b32_e64 v27, v27, 0, s[60:61]
	v_cndmask_b32_e64 v28, v28, 0, s[62:63]
	v_cndmask_b32_e64 v29, v29, 0, s[64:65]
	v_mfma_f32_32x32x16_bf16 v[32:47], v[80:83], v[68:71], v[32:47]
	v_cndmask_b32_e64 v30, v30, 0, s[66:67]
	v_cndmask_b32_e64 v31, v31, 0, s[68:69]
	v_mfma_f32_32x32x16_bf16 v[0:15], v[84:87], v[56:59], v[0:15]
	v_mfma_f32_32x32x16_bf16 v[32:47], v[84:87], v[72:75], v[32:47]
	v_mfma_f32_32x32x16_bf16 v[0:15], v[88:91], v[60:63], v[0:15]
	v_mfma_f32_32x32x16_bf16 v[32:47], v[88:91], v[76:79], v[32:47]
	s_nop 10
	v_cndmask_b32_e64 v0, v0, 0, s[38:39]
	v_cndmask_b32_e64 v1, 0, v1, s[40:41]
	v_cndmask_b32_e64 v2, v2, 0, s[42:43]
	v_cndmask_b32_e64 v3, v3, 0, s[44:45]
	v_cndmask_b32_e64 v4, v4, 0, s[46:47]
	v_cndmask_b32_e64 v5, v5, 0, s[48:49]
	v_cndmask_b32_e64 v6, v6, 0, s[50:51]
	v_cndmask_b32_e64 v7, v7, 0, s[52:53]
	v_cndmask_b32_e64 v8, v8, 0, s[54:55]
	v_cndmask_b32_e64 v9, v9, 0, s[56:57]
	v_cndmask_b32_e64 v10, v10, 0, s[58:59]
	v_cndmask_b32_e64 v11, v11, 0, s[60:61]
	v_cndmask_b32_e64 v12, v12, 0, s[62:63]
	v_cndmask_b32_e64 v13, v13, 0, s[64:65]
	v_cndmask_b32_e64 v14, v14, 0, s[66:67]
	v_cndmask_b32_e64 v15, v15, 0, s[68:69]
	v_cvt_pk_bf16_f32 v80, v0, v1
	v_cvt_pk_bf16_f32 v81, v2, v3
	v_cvt_pk_bf16_f32 v82, v4, v5
	v_cvt_pk_bf16_f32 v83, v6, v7
	v_cvt_pk_bf16_f32 v32, v32, v33
	v_cvt_pk_bf16_f32 v33, v34, v35
	v_cvt_pk_bf16_f32 v34, v36, v37
	v_cvt_pk_bf16_f32 v35, v38, v39
	v_cvt_pk_bf16_f32 v36, v16, v17
	v_cvt_pk_bf16_f32 v37, v18, v19
	v_cvt_pk_bf16_f32 v38, v20, v21
	v_cvt_pk_bf16_f32 v39, v22, v23
	v_cvt_pk_bf16_f32 v84, v8, v9
	v_cvt_pk_bf16_f32 v85, v10, v11
	v_cvt_pk_bf16_f32 v86, v12, v13
	v_cvt_pk_bf16_f32 v87, v14, v15
	v_cvt_pk_bf16_f32 v40, v40, v41
	v_cvt_pk_bf16_f32 v41, v42, v43
	v_cvt_pk_bf16_f32 v42, v44, v45
	v_cvt_pk_bf16_f32 v43, v46, v47
	v_cvt_pk_bf16_f32 v44, v24, v25
	v_cvt_pk_bf16_f32 v45, v26, v27
	v_cvt_pk_bf16_f32 v46, v28, v29
	v_cvt_pk_bf16_f32 v47, v30, v31
	v_lshl_add_u64 v[88:89], v[158:159], 0, s[0:1]
	v_mov_b64_e32 v[90:91], v[156:157]
	s_mov_b32 s0, 0
	global_load_dwordx4 v[198:201], v[90:91], off offset:-64
	global_load_dwordx4 v[202:205], v[90:91], off offset:-32
	global_load_dwordx4 v[206:209], v[90:91], off
	global_load_dwordx4 v[210:213], v[90:91], off offset:32
	global_load_dwordx2 v[214:215], v[88:89], off offset:-64
	global_load_dwordx2 v[216:217], v[88:89], off offset:-48
	global_load_dwordx2 v[224:225], v[88:89], off offset:-32
	global_load_dwordx2 v[226:227], v[88:89], off offset:-16
	global_load_dwordx2 v[228:229], v[88:89], off
	global_load_dwordx2 v[230:231], v[88:89], off offset:16
	global_load_dwordx2 v[232:233], v[88:89], off offset:32
	global_load_dwordx2 v[234:235], v[88:89], off offset:48
	s_mov_b64 s[86:87], 0x1000
	v_lshl_add_u64 v[90:91], v[90:91], 0, s[86:87]
	s_mov_b64 s[86:87], 0x100000
	v_lshl_add_u64 v[88:89], v[88:89], 0, s[86:87]
.LBB0_846:
	v_add_u32_e32 v143, s0, v119
	v_add_u32_e32 v145, s0, v117
	s_add_i32 s0, s0, 64
	s_cmpk_lg_i32 s0, 0x100
	s_waitcnt vmcnt(11)
	v_mfma_f32_32x32x16_bf16 v[0:15], v[198:201], v[48:51], 0
	v_mfma_f32_32x32x16_bf16 v[16:31], v[198:201], v[64:67], 0
	s_waitcnt vmcnt(10)
	v_mfma_f32_32x32x16_bf16 v[0:15], v[202:205], v[52:55], v[0:15]
	v_mfma_f32_32x32x16_bf16 v[16:31], v[202:205], v[68:71], v[16:31]
	s_waitcnt vmcnt(9)
	v_mfma_f32_32x32x16_bf16 v[0:15], v[206:209], v[56:59], v[0:15]
	v_mfma_f32_32x32x16_bf16 v[16:31], v[206:209], v[72:75], v[16:31]
	s_waitcnt vmcnt(8)
	v_mfma_f32_32x32x16_bf16 v[0:15], v[210:213], v[60:63], v[0:15]
	v_mfma_f32_32x32x16_bf16 v[16:31], v[210:213], v[76:79], v[16:31]
	s_waitcnt vmcnt(6)
	v_mfma_f32_32x32x16_bf16 v[0:15], v[214:217], v[80:83], v[0:15]
	v_mfma_f32_32x32x16_bf16 v[16:31], v[214:217], v[32:35], v[16:31]
	s_waitcnt vmcnt(4)
	v_mfma_f32_32x32x16_bf16 v[0:15], v[224:227], v[84:87], v[0:15]
	s_nop 11
	v_mov_b32_e32 v95, v8
	v_mfma_f32_32x32x16_bf16 v[16:31], v[224:227], v[40:43], v[16:31]
	s_waitcnt vmcnt(2)
	v_mfma_f32_32x32x16_bf16 v[16:31], v[228:231], v[36:39], v[16:31]
	s_waitcnt vmcnt(0)
	v_mfma_f32_32x32x16_bf16 v[16:31], v[232:235], v[44:47], v[16:31]
	s_cbranch_scc0 .Lglab_nopf
	global_load_dwordx4 v[198:201], v[90:91], off offset:-64
	global_load_dwordx4 v[202:205], v[90:91], off offset:-32
	global_load_dwordx4 v[206:209], v[90:91], off
	global_load_dwordx4 v[210:213], v[90:91], off offset:32
	global_load_dwordx2 v[214:215], v[88:89], off offset:-64
	global_load_dwordx2 v[216:217], v[88:89], off offset:-48
	global_load_dwordx2 v[224:225], v[88:89], off offset:-32
	global_load_dwordx2 v[226:227], v[88:89], off offset:-16
	global_load_dwordx2 v[228:229], v[88:89], off
	global_load_dwordx2 v[230:231], v[88:89], off offset:16
	global_load_dwordx2 v[232:233], v[88:89], off offset:32
	global_load_dwordx2 v[234:235], v[88:89], off offset:48
	s_mov_b64 s[86:87], 0x1000
	v_lshl_add_u64 v[90:91], v[90:91], 0, s[86:87]
	s_mov_b64 s[86:87], 0x100000
	v_lshl_add_u64 v[88:89], v[88:89], 0, s[86:87]
.Lglab_nopf:
	v_cvt_pk_bf16_f32 v168, v0, v1
	v_cvt_pk_bf16_f32 v169, v2, v3
	ds_write_b64 v143, v[168:169]
	v_cvt_pk_bf16_f32 v168, v4, v5
	v_cvt_pk_bf16_f32 v169, v6, v7
	s_nop 6
	v_cvt_pk_bf16_f32 v170, v16, v17
	v_cvt_pk_bf16_f32 v171, v18, v19
	ds_write_b64 v145, v[170:171]
	v_cvt_pk_bf16_f32 v170, v20, v21
	v_cvt_pk_bf16_f32 v171, v22, v23
	ds_write_b64 v143, v[168:169] offset:16
	ds_write_b64 v145, v[170:171] offset:16
	v_cvt_pk_bf16_f32 v168, v8, v9
	v_cvt_pk_bf16_f32 v169, v10, v11
	v_cvt_pk_bf16_f32 v170, v24, v25
	v_cvt_pk_bf16_f32 v171, v26, v27
	ds_write_b64 v143, v[168:169] offset:32
	ds_write_b64 v145, v[170:171] offset:32
	v_cvt_pk_bf16_f32 v168, v12, v13
	v_cvt_pk_bf16_f32 v169, v14, v15
	v_cvt_pk_bf16_f32 v170, v28, v29
	v_cvt_pk_bf16_f32 v171, v30, v31
	ds_write_b64 v143, v[168:169] offset:48
	ds_write_b64 v145, v[170:171] offset:48
	v_mov_b32_e32 v168, v16
	v_mov_b32_e32 v169, v0
	v_mov_b32_e32 v0, v17
	v_mov_b32_e32 v16, v18
	v_mov_b32_e32 v17, v2
	v_mov_b32_e32 v2, v19
	v_mov_b32_e32 v18, v20
	v_mov_b32_e32 v19, v4
	v_mov_b32_e32 v4, v21
	v_mov_b32_e32 v20, v22
	v_mov_b32_e32 v21, v6
	v_mov_b32_e32 v6, v23
	v_pk_fma_f32 v[22:23], v[168:169], v[168:169], v[92:93]
	v_mov_b32_e32 v94, v24
	v_pk_fma_f32 v[0:1], v[0:1], v[0:1], v[22:23]
	v_mov_b32_e32 v8, v25
	v_pk_fma_f32 v[0:1], v[16:17], v[16:17], v[0:1]
	s_nop 0
	v_pk_fma_f32 v[0:1], v[2:3], v[2:3], v[0:1]
	v_mov_b32_e32 v2, v26
	v_pk_fma_f32 v[0:1], v[18:19], v[18:19], v[0:1]
	v_mov_b32_e32 v3, v10
	v_pk_fma_f32 v[0:1], v[4:5], v[4:5], v[0:1]
	v_mov_b32_e32 v10, v27
	v_pk_fma_f32 v[0:1], v[20:21], v[20:21], v[0:1]
	v_mov_b32_e32 v4, v28
	v_pk_fma_f32 v[0:1], v[6:7], v[6:7], v[0:1]
	v_mov_b32_e32 v5, v12
	v_pk_fma_f32 v[0:1], v[94:95], v[94:95], v[0:1]
	v_mov_b32_e32 v12, v29
	v_pk_fma_f32 v[0:1], v[8:9], v[8:9], v[0:1]
	v_mov_b32_e32 v6, v30
	v_pk_fma_f32 v[0:1], v[2:3], v[2:3], v[0:1]
	v_mov_b32_e32 v7, v14
	v_pk_fma_f32 v[0:1], v[10:11], v[10:11], v[0:1]
	v_mov_b32_e32 v14, v31
	v_pk_fma_f32 v[0:1], v[4:5], v[4:5], v[0:1]
	s_nop 0
	v_pk_fma_f32 v[0:1], v[12:13], v[12:13], v[0:1]
	s_nop 0
	v_pk_fma_f32 v[0:1], v[6:7], v[6:7], v[0:1]
	s_nop 0
	v_pk_fma_f32 v[92:93], v[14:15], v[14:15], v[0:1]
	s_cbranch_scc1 .LBB0_846
	ds_bpermute_b32 v1, v111, v93
	ds_bpermute_b32 v0, v111, v92
	s_and_saveexec_b64 s[86:87], s[70:71]
	s_cbranch_execz .LBB0_849
	s_waitcnt lgkmcnt(0)
	v_pk_add_f32 v[0:1], v[92:93], v[0:1]
	s_brev_b32 s0, 60
	v_pk_fma_f32 v[0:1], v[0:1], s[0:1], v[166:167] op_sel_hi:[1,0,0]
	s_nop 0
	v_mul_f32_e32 v2, 0x4b800000, v1
	v_cmp_gt_f32_e32 vcc, s79, v1
	v_cmp_gt_f32_e64 s[0:1], s79, v0
	s_nop 0
	v_cndmask_b32_e32 v1, v1, v2, vcc
	v_rsq_f32_e32 v1, v1
	v_mul_f32_e32 v2, 0x4b800000, v0
	v_cndmask_b32_e64 v0, v0, v2, s[0:1]
	v_rsq_f32_e32 v0, v0
	v_mul_f32_e32 v2, 0x45800000, v1
	v_cndmask_b32_e32 v1, v1, v2, vcc
	ds_write_b32 v113, v1 offset:17408
	v_mul_f32_e32 v1, 0x45800000, v0
	v_cndmask_b32_e64 v0, v0, v1, s[0:1]
	ds_write_b32 v115, v0 offset:17536
